# cg grid.sync after the prologue replaced by a copy of the XCD atomic barrier; topk Q-tile loads issued together
# speedup vs baseline: 1.1803x; 1.0205x over previous
; #define LAS __attribute__((address_space(3)))
; __global__ void __launch_bounds__(NTHR, 2) mega(Params p) {
;     ...
;   cg::grid_group grid = cg::this_grid();
;   volatile LAS unsigned* bst = (volatile LAS unsigned*)(smem + LDS_BYTES - 32);
;   if (threadIdx.x == 0) { bst[0] = 0u; bst[1] = 0u; }
;   __syncthreads();
;   const XcdBarrier bar = xcd_barrier_post(WSP(unsigned, OFF_BAR), bst);
;   for (int rep = 0; rep < 1 + (REP_MASK & 1); ++rep) { if (PH_MASK & 1) phase_prologue(p, bid, nblk, smem); }
;   grid.sync();
.LBB0_341:
	s_or_b64 exec, exec, s[12:13]
	v_lshrrev_b32_e32 v1, 20, v0
	v_lshrrev_b32_e32 v0, 10, v0
	v_or_b32_e32 v0, v0, v1
	s_movk_i32 s0, 0x3ff
	v_and_or_b32 v0, v0, s0, v218
	v_cmp_eq_u32_e32 vcc, 0, v0
	v_writelane_b32 v254, s20, 59
	s_nop 1
	v_writelane_b32 v254, s21, 60
	v_readlane_b32 s8, v253, 0
	s_lshl_b32 s12, s8, 2
	s_lshl_b32 s10, s54, 2
	s_add_u32 s0, s96, 0x1be04000
	s_addc_u32 s1, s97, 0
	s_add_u32 s6, s96, 0xa200000
	v_writelane_b32 v253, s0, 19
	s_addc_u32 s7, s97, 0
	s_mov_b32 s87, 0
	v_writelane_b32 v253, s1, 20
	s_add_u32 s0, s96, 0x17a00000
	s_addc_u32 s1, s97, 0
	v_writelane_b32 v253, s0, 21
	v_mbcnt_lo_u32_b32 v0, -1, 0
	v_mbcnt_hi_u32_b32 v215, -1, v0
	v_writelane_b32 v253, s1, 22
	s_add_u32 s0, s96, 0x1c110300
	s_addc_u32 s1, s97, 0
	v_writelane_b32 v253, s0, 23
	v_and_b32_e32 v216, 64, v215
	v_mov_b32_e32 v173, 0
	v_writelane_b32 v253, s1, 24
	s_add_u32 s0, s96, 0x1c110500
	s_addc_u32 s1, s97, 0
	v_writelane_b32 v253, s0, 25
	v_mov_b32_e32 v208, 0x358637bd
	v_mov_b32_e32 v204, 1
	v_writelane_b32 v253, s1, 26
	s_add_u32 s0, s96, 0x1c110600
	s_addc_u32 s1, s97, 0
	v_writelane_b32 v253, s0, 27
	v_mov_b32_e32 v205, 0x3ecc95a3
	v_add_u32_e32 v213, 64, v216
	v_writelane_b32 v253, s1, 28
	s_add_u32 s0, s96, 0x1c110700
	s_addc_u32 s1, s97, 0
	v_writelane_b32 v253, s0, 29
	v_xor_b32_e32 v209, 32, v215
	v_xor_b32_e32 v210, 16, v215
	v_writelane_b32 v253, s1, 30
	s_add_u32 s0, s96, 0x1c110800
	s_addc_u32 s1, s97, 0
	v_writelane_b32 v253, s0, 31
	v_xor_b32_e32 v225, 8, v215
	v_xor_b32_e32 v212, 4, v215
	v_writelane_b32 v253, s1, 32
	s_add_u32 s0, s96, 0x1c110900
	s_addc_u32 s1, s97, 0
	v_writelane_b32 v253, s0, 33
	v_xor_b32_e32 v203, 2, v215
	v_xor_b32_e32 v224, 1, v215
	v_writelane_b32 v253, s1, 34
	s_add_u32 s0, s96, 0x1c110a00
	s_addc_u32 s1, s97, 0
	v_writelane_b32 v253, s0, 35
	v_mov_b32_e32 v217, 0x7f800000
	v_mov_b32_e32 v174, 0x3f317218
	v_writelane_b32 v253, s1, 36
	s_add_u32 s0, s96, 0x1c110b00
	s_addc_u32 s1, s97, 0
	v_writelane_b32 v253, s0, 37
	s_movk_i32 s76, 0x7fff
	s_mov_b32 s77, 0xffff0000
	v_writelane_b32 v253, s1, 38
	s_add_u32 s0, s96, 0x1c110c00
	s_addc_u32 s1, s97, 0
	v_writelane_b32 v253, s0, 39
	s_movk_i32 s9, 0x1200
	s_mov_b32 s58, 0x42b17218
	v_writelane_b32 v253, s1, 40
	s_add_u32 s0, s96, 0x1c110d00
	s_addc_u32 s1, s97, 0
	v_writelane_b32 v253, s0, 41
	s_mov_b32 s59, 0x7f800000
	s_movk_i32 s52, 0x110
	v_writelane_b32 v253, s1, 42
	s_add_u32 s0, s96, 0x1c110e00
	s_addc_u32 s1, s97, 0
	v_writelane_b32 v253, s0, 43
	s_mov_b32 s53, 0x41a00000
	s_mov_b32 s14, 0x3f2aaaab
	v_writelane_b32 v253, s1, 44
	s_add_u32 s0, s96, 0x1c110f00
	s_addc_u32 s1, s97, 0
	v_writelane_b32 v253, s0, 45
	s_mov_b32 s15, 0x3f317218
	s_mov_b64 s[70:71], 0
	v_writelane_b32 v253, s1, 46
	s_add_u32 s0, s96, 0x1c111000
	s_addc_u32 s1, s97, 0
	v_writelane_b32 v253, s0, 47
	s_mov_b32 s24, s87
	s_barrier
; #define LAS __attribute__((address_space(3)))
; DI unsigned xb_ld(unsigned* p) { return __hip_atomic_load(p, __ATOMIC_RELAXED, __HIP_MEMORY_SCOPE_AGENT); }
; DI unsigned xb_add(unsigned* p, unsigned v) { return __hip_atomic_fetch_add(p, v, __ATOMIC_RELAXED, __HIP_MEMORY_SCOPE_AGENT); }
; DI unsigned xb_xcc_id() { return (unsigned)__builtin_amdgcn_s_getreg((3 << 11) | 20) & 0xFu; }
; #define GBAR() xcd_barrier(bar)
; DI XcdBarrier xcd_barrier_post(unsigned* bar, volatile LAS unsigned* st) {
;   XcdBarrier b; b.bar = bar; b.x = xb_xcc_id(); b.st = st;
;   if (threadIdx.x == 0) (void)xb_add(&bar[XB_XCNT(b.x)], 1u);
;   return b;
; }
; DI void xcd_barrier_complete(unsigned* bar, unsigned x, unsigned& nloc, unsigned& nx) {
;   const unsigned G = gridDim.x * gridDim.y * gridDim.z;
;   unsigned sum, cnt, mine, sp = 0u;
;   for (;;) {
;     sum = 0u; cnt = 0u; mine = 0u;
; #pragma unroll
;     for (unsigned j = 0; j < 16; ++j) { const unsigned c = xb_ld(&bar[XB_XCNT(j)]); sum += c; cnt += (c > 0u) ? 1u : 0u; mine = (j == x) ? c : mine; }
;     if (sum == G) break;
;     __builtin_amdgcn_s_sleep(1);
;     if ((++sp & 255u) == 0u) { if (xb_ld(&bar[XB_TMO])) break; if (sp > XB_SPIN_CAP) { atomicAdd(&bar[XB_TMO], 1u); break; } }
;   }
;   nloc = mine > 0u ? mine : 1u; nx = cnt > 0u ? cnt : 1u;
; }
; __global__ void __launch_bounds__(NTHR, 2) mega(Params p) {
;     ...
;   const XcdBarrier bar = xcd_barrier_post(WSP(unsigned, OFF_BAR), bst);
;   for (int rep = 0; rep < 1 + (REP_MASK & 1); ++rep) { if (PH_MASK & 1) phase_prologue(p, bid, nblk, smem); }
;   grid.sync();
;     ...
; #pragma nounroll
;   for (int l = 0; l < 2; ++l) {
;     for (int xs = 0; xs < EXTRA_SYNCS; ++xs) GBAR();
;     run_stage<0>(p, l, bid, nblk, smem); GBAR();
	v_writelane_b32 v253, s1, 48
	s_add_u32 s0, s96, 0x1c111100
	s_addc_u32 s1, s97, 0
	v_writelane_b32 v253, s0, 49
	s_nop 1
	v_writelane_b32 v253, s1, 50
	s_add_u32 s0, s96, 0x1c111200
	s_addc_u32 s1, s97, 0
	v_writelane_b32 v253, s0, 51
	s_nop 1
	v_writelane_b32 v253, s1, 52
	s_add_u32 s0, s96, 0x1c111300
	s_addc_u32 s1, s97, 0
	v_writelane_b32 v253, s0, 53
	s_nop 1
	v_writelane_b32 v253, s1, 54
	s_add_u32 s0, s96, 0x1c111400
	s_addc_u32 s1, s97, 0
	v_writelane_b32 v253, s0, 55
	s_cmp_eq_u32 s50, 15
	s_nop 0
	v_writelane_b32 v253, s1, 56
	s_cselect_b64 s[0:1], -1, 0
	v_writelane_b32 v253, s0, 57
	s_cmp_eq_u32 s50, 14
	s_nop 0
	v_writelane_b32 v253, s1, 58
	s_cselect_b64 s[0:1], -1, 0
	v_writelane_b32 v253, s0, 59
	s_cmp_eq_u32 s50, 13
	s_nop 0
	v_writelane_b32 v253, s1, 60
	s_cselect_b64 s[0:1], -1, 0
	v_writelane_b32 v253, s0, 61
	s_cmp_eq_u32 s50, 12
	s_nop 0
	v_writelane_b32 v253, s1, 62
	s_cselect_b64 s[0:1], -1, 0
	v_writelane_b32 v253, s0, 63
	s_cmp_eq_u32 s50, 11
	s_nop 0
	v_writelane_b32 v255, s1, 0
	s_cselect_b64 s[0:1], -1, 0
	v_writelane_b32 v255, s0, 1
	s_cmp_eq_u32 s50, 10
	s_nop 0
	v_writelane_b32 v255, s1, 2
	s_cselect_b64 s[0:1], -1, 0
	v_writelane_b32 v255, s0, 3
	s_cmp_eq_u32 s50, 9
	s_nop 0
	v_writelane_b32 v255, s1, 4
	s_cselect_b64 s[0:1], -1, 0
	v_writelane_b32 v255, s0, 5
	s_cmp_eq_u32 s50, 8
	s_nop 0
	v_writelane_b32 v255, s1, 6
	s_cselect_b64 s[0:1], -1, 0
	v_writelane_b32 v255, s0, 7
	s_cmp_eq_u32 s50, 7
	s_nop 0
	v_writelane_b32 v255, s1, 8
	s_cselect_b64 s[0:1], -1, 0
	v_writelane_b32 v255, s0, 9
	s_cmp_eq_u32 s50, 6
	s_nop 0
	v_writelane_b32 v255, s1, 10
	s_cselect_b64 s[0:1], -1, 0
	v_writelane_b32 v255, s0, 11
	s_cmp_eq_u32 s50, 5
	s_nop 0
	v_writelane_b32 v255, s1, 12
	s_cselect_b64 s[0:1], -1, 0
	v_writelane_b32 v255, s0, 13
	s_cmp_eq_u32 s50, 4
	s_nop 0
	v_writelane_b32 v255, s1, 14
	s_cselect_b64 s[0:1], -1, 0
	v_writelane_b32 v255, s0, 15
	s_cmp_eq_u32 s50, 3
	s_nop 0
	v_writelane_b32 v255, s1, 16
	s_cselect_b64 s[0:1], -1, 0
	v_writelane_b32 v255, s0, 17
	s_cmp_eq_u32 s50, 2
	s_nop 0
	v_writelane_b32 v255, s1, 18
	s_cselect_b64 s[0:1], -1, 0
	v_writelane_b32 v255, s0, 19
	s_cmp_eq_u32 s50, 1
	s_nop 0
	v_writelane_b32 v255, s1, 20
	s_cselect_b64 s[0:1], -1, 0
	v_writelane_b32 v255, s0, 21
	s_cmp_eq_u32 s50, 0
	s_nop 0
	v_writelane_b32 v255, s1, 22
	s_cselect_b64 s[0:1], -1, 0
	v_writelane_b32 v255, s0, 23
	s_nop 1
	v_writelane_b32 v255, s1, 24
	s_lshl_b32 s0, s50, 8
	s_add_u32 s0, s36, s0
	s_addc_u32 s1, s37, 0
	s_add_u32 s2, s0, 0x1400
	s_addc_u32 s3, s1, 0
	v_writelane_b32 v255, s2, 25
	s_add_u32 s0, s0, 0x2400
	s_addc_u32 s1, s1, 0
	v_writelane_b32 v255, s3, 26
	v_writelane_b32 v255, s0, 27
	s_nop 1
	v_writelane_b32 v255, s1, 28
	s_add_u32 s0, s96, 0x1c113500
	s_addc_u32 s1, s97, 0
	v_writelane_b32 v255, s0, 29
	s_nop 1
	v_writelane_b32 v255, s1, 30
	s_add_u32 s0, s96, 0x1c113600
	s_addc_u32 s1, s97, 0
	v_writelane_b32 v255, s0, 31
	s_nop 1
	v_writelane_b32 v255, s1, 32
	s_and_b32 s0, s8, 7
	s_ashr_i32 s1, s54, 3
	s_mul_i32 s0, s1, s0
	s_ashr_i32 s1, s8, 3
	s_add_i32 s0, s0, s1
	s_and_b32 s1, s54, 7
	s_add_u32 s2, s96, 0x3600000
	s_addc_u32 s3, s97, 0
	s_add_u32 s60, s96, 0x5a00000
	s_addc_u32 s61, s97, 0
	s_add_u32 s68, s96, 0x13200000
	v_writelane_b32 v255, s2, 33
	s_addc_u32 s69, s97, 0
	s_nop 0
	v_writelane_b32 v255, s3, 34
	s_add_u32 s2, s96, 0x1bed0000
	s_addc_u32 s3, s97, 0
	v_writelane_b32 v255, s2, 35
	s_cmp_eq_u32 s1, 0
	s_cselect_b32 s0, s0, s8
	v_writelane_b32 v255, s3, 36
	s_cmpk_lt_i32 s8, 0xd80
	v_writelane_b32 v255, s0, 37
	s_cselect_b64 s[0:1], -1, 0
	v_writelane_b32 v255, s0, 38
	s_nop 1
	v_writelane_b32 v255, s1, 39
	s_add_u32 s0, s96, 0xea00000
	s_addc_u32 s1, s97, 0
	v_writelane_b32 v255, s0, 40
	s_nop 1
	v_writelane_b32 v255, s1, 41
	s_add_u32 s0, s96, 0x16800000
	s_addc_u32 s1, s97, 0
	v_writelane_b32 v255, s0, 42
	s_bitcmp0_b32 s8, 0
	s_nop 0
	v_writelane_b32 v255, s1, 43
	s_cselect_b64 s[0:1], -1, 0
	s_ashr_i32 s2, s8, 1
	s_cmpk_lt_i32 s2, 0x100
	v_writelane_b32 v255, s2, 44
	s_cselect_b64 s[2:3], -1, 0
	s_and_b64 s[0:1], s[0:1], s[2:3]
	v_writelane_b32 v255, s0, 45
	s_mov_b32 s2, 0x3fb8aa3b
	s_mov_b32 s3, 0xc2ce8ed0
	v_writelane_b32 v255, s1, 46
	s_mul_i32 s0, s33, s55
	s_mul_i32 s55, s0, s54
	s_add_i32 s0, s54, 1
	s_ashr_i32 s0, s0, 1
	s_add_u32 s4, s96, 0x1c113700
	s_addc_u32 s5, s97, 0
	v_writelane_b32 v255, s0, 47
	s_add_u32 s0, s96, 0x1c110000
	v_writelane_b32 v255, s0, 48
	s_addc_u32 s0, s97, 0
	v_writelane_b32 v255, s0, 49
	s_add_u32 s0, s96, 0x15600000
	s_addc_u32 s1, s97, 0
	v_writelane_b32 v255, s0, 50
	s_mov_b32 s33, 0x38e38e39
	s_nop 0
	v_writelane_b32 v255, s1, 51
	s_add_u32 s0, s96, 0xfa00000
	s_addc_u32 s1, s97, 0
	v_writelane_b32 v255, s0, 52
	s_nop 1
	v_writelane_b32 v255, s1, 53
	s_nop 0
	v_readlane_b32 s0, v255, 54
	s_addk_i32 s0, 0xfe00
	s_nop 0
	v_writelane_b32 v255, s0, 55
	s_add_u32 s0, s96, 0x156002c0
	s_addc_u32 s1, s97, 0
	v_writelane_b32 v255, s0, 56
	s_ashr_i32 s13, s12, 31
	s_ashr_i32 s11, s10, 31
	v_writelane_b32 v255, s1, 57
	v_writelane_b32 v255, s12, 58
	s_lshl_b32 s0, s8, 14
	s_ashr_i32 s19, s18, 31
	v_writelane_b32 v255, s13, 59
	v_writelane_b32 v255, s0, 60
	s_lshl_b32 s0, s54, 14
	v_writelane_b32 v255, s0, 61
	s_add_i32 s0, 0, 0x11fe0
	v_writelane_b32 v255, s0, 62
	s_add_i32 s0, 0, 0x11fe4
	v_writelane_b32 v255, s0, 63
	s_add_i32 s0, 0, 0x8800
	v_writelane_b32 v254, s0, 0
	s_add_i32 s0, 0, 0x11ff0
	v_writelane_b32 v254, s0, 1
	s_lshl_b64 s[0:1], s[10:11], 11
	v_writelane_b32 v254, s0, 2
	s_movk_i32 s8, 0x50
	s_mov_b32 s12, 0x33800000
	v_writelane_b32 v254, s1, 3
	s_lshl_b64 s[0:1], s[10:11], 10
	v_writelane_b32 v254, s0, 4
	s_nop 1
	v_writelane_b32 v254, s1, 5
	s_lshl_b64 s[0:1], s[18:19], 4
	v_writelane_b32 v254, s0, 6
	s_nop 1
	v_writelane_b32 v254, s1, 7
	s_mov_b64 s[0:1], -1
	v_writelane_b32 v254, s0, 8
	s_nop 1
	v_writelane_b32 v254, s1, 9
	s_mov_b32 s0, s18
	v_writelane_b32 v254, s0, 10
	s_nop 1
	v_writelane_b32 v254, s1, 11
	v_writelane_b32 v254, s55, 12

; DI unsigned xb_ld(unsigned* p) { return __hip_atomic_load(p, __ATOMIC_RELAXED, __HIP_MEMORY_SCOPE_AGENT); }
; DI unsigned xb_add(unsigned* p, unsigned v) { return __hip_atomic_fetch_add(p, v, __ATOMIC_RELAXED, __HIP_MEMORY_SCOPE_AGENT); }
; #define XB_SPIN(cond, bar) do { unsigned _sp = 0; while (cond) { __builtin_amdgcn_s_sleep(1); \
;     if ((++_sp & 255u) == 0u) { if (xb_ld(&(bar)[XB_TMO])) break; if (_sp > XB_SPIN_CAP) { atomicAdd(&(bar)[XB_TMO], 1u); break; } } } } while (0)
; DI void xcd_barrier(const XcdBarrier& b) {
;   asm volatile("s_waitcnt vmcnt(0)" ::: "memory");
;   __syncthreads();
;   if (threadIdx.x == 0) {
;     unsigned* bar = b.bar;
;     __builtin_amdgcn_s_waitcnt(0);
;     unsigned nloc = b.st[0], nx = b.st[1];
;     if (nloc == 0u) { xcd_barrier_complete(bar, b.x, nloc, nx); b.st[0] = nloc; b.st[1] = nx; }
;     const unsigned old = xb_add(&bar[XB_XSUB(b.x)], 1u);
;     const unsigned gen = old / nloc;
;     if (old + 1u == (gen + 1u) * nloc) {
;       __builtin_amdgcn_fence(__ATOMIC_RELEASE, "agent");
;       asm volatile("s_waitcnt vmcnt(0)" ::: "memory");
;       const unsigned og = xb_add(&bar[XB_TOP], 1u);
;       const unsigned tg = og / nx;
;       if (og + 1u == (tg + 1u) * nx) xb_add(&bar[XB_TOPGEN], 1u);
;       else XB_SPIN(xb_ld(&bar[XB_TOPGEN]) == tg, bar);
;       __builtin_amdgcn_fence(__ATOMIC_ACQUIRE, "agent");
;       xb_add(&bar[XB_XGEN(b.x)], 1u);
;       asm volatile("s_waitcnt vmcnt(0)" ::: "memory");
;     } else {
;       XB_SPIN(xb_ld(&bar[XB_XGEN(b.x)]) == gen, bar);
;       __builtin_amdgcn_fence(__ATOMIC_ACQUIRE, "agent");
;       asm volatile("s_waitcnt vmcnt(0)" ::: "memory");
;     }
;   }
;   __syncthreads();
; }
.Lgs_1321:
	s_or_b64 exec, exec, s[34:35]
	s_waitcnt lgkmcnt(0)
	v_mov_b32_e32 v0, v218
	v_mov_b32_e32 v1, v218
	s_barrier
	s_branch .LBB0_355

; DI int TID() { int t = threadIdx.x; asm volatile("" : "+v"(t)); return t; }
; template <bool SWAP, int MI, class AF, class BF, class EF>
; DI void gemm_tile(const AF& af, const BF& bfn, const EF& ef, int m0, int n0, int K, char* smem) {
;   constexpr int AROWS = MI * 64;
;   u16* As = (u16*)smem;
;   u16* Bs = As + 2 * AROWS * 40;
;   const int tid = TID(), lane = tid & 63, w = tid >> 6;
;   const int wm = w >> 1, wn = w & 1, l32 = lane & 31, h = lane >> 5;
;   const int lrow = (tid >> 6) * 16 + ((tid >> 5) & 1) * 8 + ((tid >> 2) & 1) * 4 + ((tid >> 3) & 3), lk = (tid & 3) * 8;
;   f32x16 acc[MI][2];
; #pragma unroll
;   for (int i = 0; i < MI; ++i)
; #pragma unroll
;     for (int j = 0; j < 2; ++j)
; #pragma unroll
;       for (int r = 0; r < 16; ++r) acc[i][j][r] = 0.f;
;   u32x4 ra[MI], rb[2];
;   const int nk = K >> 5;
; #pragma unroll
;   for (int i = 0; i < MI; ++i) ra[i] = *(const u32x4*)af(m0 + lrow + 64 * i, lk);
; #pragma unroll
;   for (int i = 0; i < 2; ++i) rb[i] = *(const u32x4*)bfn(n0 + lrow + 64 * i, lk);
; #pragma unroll
;   for (int i = 0; i < MI; ++i) *(u32x4*)&As[(lrow + 64 * i) * 40 + lk] = ra[i];
; #pragma unroll
;   for (int i = 0; i < 2; ++i) *(u32x4*)&Bs[(lrow + 64 * i) * 40 + lk] = rb[i];
;   {
;     const int k1 = (nk > 1) ? 32 + lk : lk;
; #pragma unroll
;     for (int i = 0; i < MI; ++i) ra[i] = *(const u32x4*)af(m0 + lrow + 64 * i, k1);
; #pragma unroll
;     for (int i = 0; i < 2; ++i) rb[i] = *(const u32x4*)bfn(n0 + lrow + 64 * i, k1);
;   }
;   __syncthreads();
; DI void phase_q(const Params& p, int l, int bid, int nblk, char* smem) {
;     ...
;   const int ntile = (l == 1 ? NB * 8 : ROWS / 256) * 16;
;   const int vb = (nblk % 8 == 0) ? (bid & 7) * (nblk >> 3) + (bid >> 3) : bid;
;   for (int t = vb; t < ntile; t += nblk) {
;     const int mi = t >> 4, nt = t & 15;
;     const int mt = (l == 1) ? (mi >> 3) * 9 + (mi & 7) + 1 : mi;
;     gemm_tile<true, 4>(af, bfn, ef, mt * 256, nt * 128, 1024, smem);
.LBB0_1390:
	s_lshl_b32 s78, s35, 8
	s_and_b32 s79, s34, 15
	s_lshl_b32 s79, s79, 7
	v_lshrrev_b32_e32 v128, 6, v218
	v_bfe_u32 v129, v218, 5, 1
	v_bfe_u32 v130, v218, 2, 1
	v_bfe_u32 v131, v218, 3, 2
	v_lshlrev_b32_e32 v132, 4, v128
	v_lshl_add_u32 v132, v129, 3, v132
	v_lshl_add_u32 v132, v130, 2, v132
	v_add_u32_e32 v132, v132, v131
	v_and_b32_e32 v133, 3, v218
	v_lshlrev_b32_e32 v133, 4, v133
	v_lshl_add_u32 v200, v132, 11, v133
	v_mul_u32_u24_e32 v134, 80, v132
	v_add_u32_e32 v202, v134, v133
	v_and_b32_e32 v135, 31, v218
	v_lshrrev_b32_e32 v136, 7, v218
	v_bfe_u32 v137, v218, 6, 1
	v_lshl_add_u32 v136, v136, 7, v135
	v_lshl_add_u32 v137, v137, 6, v135
	v_mul_u32_u24_e32 v136, 80, v136
	v_mul_u32_u24_e32 v137, 80, v137
	v_lshl_add_u32 v206, v129, 4, v136
	v_lshl_add_u32 v207, v129, 4, v137
	s_add_i32 s66, s78, 0
	s_lshl_b32 s66, s66, 11
	s_add_u32 s36, s6, s66
	s_addc_u32 s37, s7, 0
	s_add_i32 s66, s78, 64
	s_lshl_b32 s66, s66, 11
	s_add_u32 s38, s6, s66
	s_addc_u32 s39, s7, 0
	s_add_i32 s66, s78, 128
	s_lshl_b32 s66, s66, 11
	s_add_u32 s42, s6, s66
	s_addc_u32 s43, s7, 0
	s_add_i32 s66, s78, 192
	s_lshl_b32 s66, s66, 11
	s_add_u32 s46, s6, s66
	s_addc_u32 s47, s7, 0
	s_add_i32 s66, s79, 0
	s_lshl_b32 s66, s66, 11
	s_add_u32 s48, s0, s66
	s_addc_u32 s49, s1, 0
	s_add_i32 s66, s79, 64
	s_lshl_b32 s66, s66, 11
	s_add_u32 s50, s0, s66
	s_addc_u32 s51, s1, 0
	v_mov_b64_e32 v[0:1], 0
	v_mov_b64_e32 v[2:3], 0
	v_mov_b64_e32 v[4:5], 0
	v_mov_b64_e32 v[6:7], 0
	v_mov_b64_e32 v[8:9], 0
	v_mov_b64_e32 v[10:11], 0
	v_mov_b64_e32 v[12:13], 0
	v_mov_b64_e32 v[14:15], 0
	v_mov_b64_e32 v[16:17], 0
	v_mov_b64_e32 v[18:19], 0
	v_mov_b64_e32 v[20:21], 0
	v_mov_b64_e32 v[22:23], 0
	v_mov_b64_e32 v[24:25], 0
	v_mov_b64_e32 v[26:27], 0
	v_mov_b64_e32 v[28:29], 0
	v_mov_b64_e32 v[30:31], 0
	v_mov_b64_e32 v[32:33], 0
	v_mov_b64_e32 v[34:35], 0
	v_mov_b64_e32 v[36:37], 0
	v_mov_b64_e32 v[38:39], 0
	v_mov_b64_e32 v[40:41], 0
	v_mov_b64_e32 v[42:43], 0
	v_mov_b64_e32 v[44:45], 0
	v_mov_b64_e32 v[46:47], 0
	v_mov_b64_e32 v[48:49], 0
	v_mov_b64_e32 v[50:51], 0
	v_mov_b64_e32 v[52:53], 0
	v_mov_b64_e32 v[54:55], 0
	v_mov_b64_e32 v[56:57], 0
	v_mov_b64_e32 v[58:59], 0
	v_mov_b64_e32 v[60:61], 0
	v_mov_b64_e32 v[62:63], 0
	v_mov_b64_e32 v[64:65], 0
	v_mov_b64_e32 v[66:67], 0
	v_mov_b64_e32 v[68:69], 0
	v_mov_b64_e32 v[70:71], 0
	v_mov_b64_e32 v[72:73], 0
	v_mov_b64_e32 v[74:75], 0
	v_mov_b64_e32 v[76:77], 0
	v_mov_b64_e32 v[78:79], 0
	v_mov_b64_e32 v[80:81], 0
	v_mov_b64_e32 v[82:83], 0
	v_mov_b64_e32 v[84:85], 0
	v_mov_b64_e32 v[86:87], 0
	v_mov_b64_e32 v[88:89], 0
	v_mov_b64_e32 v[90:91], 0
	v_mov_b64_e32 v[92:93], 0
	v_mov_b64_e32 v[94:95], 0
	v_mov_b64_e32 v[96:97], 0
	v_mov_b64_e32 v[98:99], 0
	v_mov_b64_e32 v[100:101], 0
	v_mov_b64_e32 v[102:103], 0
	v_mov_b64_e32 v[104:105], 0
	v_mov_b64_e32 v[106:107], 0
	v_mov_b64_e32 v[108:109], 0
	v_mov_b64_e32 v[110:111], 0
	v_mov_b64_e32 v[112:113], 0
	v_mov_b64_e32 v[114:115], 0
	v_mov_b64_e32 v[116:117], 0
	v_mov_b64_e32 v[118:119], 0
	v_mov_b64_e32 v[120:121], 0
	v_mov_b64_e32 v[122:123], 0
	v_mov_b64_e32 v[124:125], 0
	v_mov_b64_e32 v[126:127], 0
	s_mov_b32 s64, 0
	v_add_u32_e32 v201, s64, v200
	global_load_dwordx4 v[128:131], v201, s[36:37]
	global_load_dwordx4 v[152:155], v201, s[36:37] offset:64
	global_load_dwordx4 v[132:135], v201, s[38:39]
	global_load_dwordx4 v[156:159], v201, s[38:39] offset:64
	global_load_dwordx4 v[136:139], v201, s[42:43]
	global_load_dwordx4 v[160:163], v201, s[42:43] offset:64
	global_load_dwordx4 v[140:143], v201, s[46:47]
	global_load_dwordx4 v[164:167], v201, s[46:47] offset:64
	global_load_dwordx4 v[144:147], v201, s[48:49]
	global_load_dwordx4 v[168:171], v201, s[48:49] offset:64
	global_load_dwordx4 v[148:151], v201, s[50:51]
	global_load_dwordx4 v[176:179], v201, s[50:51] offset:64
	s_add_i32 s64, s64, 0x80
	s_movk_i32 s65, 16
	s_waitcnt vmcnt(0)
	ds_write_b128 v202, v[128:131] offset:0
	ds_write_b128 v202, v[132:135] offset:5120
	ds_write_b128 v202, v[136:139] offset:10240
	ds_write_b128 v202, v[140:143] offset:15360
	ds_write_b128 v202, v[144:147] offset:40960
	ds_write_b128 v202, v[148:151] offset:46080
	s_waitcnt lgkmcnt(0)
	s_barrier
	ds_read_b128 v[196:199], v207 offset:40960
	ds_read_b128 v[228:231], v207 offset:43520
	ds_read_b128 v[180:183], v206 offset:0
	ds_read_b128 v[184:187], v206 offset:2560
	ds_read_b128 v[188:191], v206 offset:5120
	ds_read_b128 v[192:195], v206 offset:7680

; DI void phase_topk(const Params& p, int l, int bid, int nblk, char* smem) {
;     ...
;     const u16* kb = WSP(const u16, OFF_K12) + (size_t)(l * 2 + (hh & 1)) * 16384;
;     bf16x8 kfr[8];
; #pragma unroll
;     for (int ks = 0; ks < 8; ++ks) kfr[ks] = *(const bf16x8*)&kb[(w * 32 + l32) * 128 + ks * 16 + h * 8];
;     __builtin_amdgcn_sched_barrier(0);
; #pragma unroll
;     for (int i = 0; i < 4; ++i) {
;       const int q = tid + 256 * i, r = q >> 4, ch = q & 15;
;       *(uint4*)&qs[r * 136 + ch * 8] = *(const uint4*)&Q[(size_t)(row0 + r) * 2048 + hh * 128 + ch * 8];
;     }
;     __syncthreads();
;     f32x16 acc[2];
; #pragma unroll
;     for (int i = 0; i < 2; ++i)
; #pragma unroll
;       for (int r = 0; r < 16; ++r) acc[i][r] = 0.f;
; #pragma unroll
;     for (int ks = 0; ks < 8; ++ks) {
;       const bf16x8 bq = kfr[ks];
;       const bf16x8 a0 = *(const bf16x8*)&qs[(l32) * 136 + ks * 16 + h * 8];
;       const bf16x8 a1 = *(const bf16x8*)&qs[(32 + l32) * 136 + ks * 16 + h * 8];
;       acc[0] = __builtin_amdgcn_mfma_f32_32x32x16_bf16(a0, bq, acc[0], 0, 0, 0);
;       acc[1] = __builtin_amdgcn_mfma_f32_32x32x16_bf16(a1, bq, acc[1], 0, 0, 0);
;     }
; #pragma unroll
;     for (int mt = 0; mt < 2; ++mt)
; #pragma unroll
;       for (int i = 0; i < 16; ++i) {
;         const int r = mt * 32 + (i & 3) + 8 * (i >> 2) + 4 * h;
;         sc[r * 133 + w * 33 + l32] = acc[mt][i];
;       }
;     __syncthreads();
.LBB0_1451:
	s_and_b32 s35, s37, 0x4000
	s_or_b32 s35, s35, s36
	s_lshl_b32 s86, s35, 1
	v_lshl_add_u64 v[4:5], v[42:43], 0, s[86:87]
	global_load_dwordx4 v[0:3], v[4:5], off
	global_load_dwordx4 v[50:53], v[4:5], off offset:32
	global_load_dwordx4 v[54:57], v[4:5], off offset:64
	global_load_dwordx4 v[58:61], v[4:5], off offset:96
	global_load_dwordx4 v[62:65], v[4:5], off offset:128
	global_load_dwordx4 v[66:69], v[4:5], off offset:160
	global_load_dwordx4 v[70:73], v[4:5], off offset:192
	global_load_dwordx4 v[74:77], v[4:5], off offset:224
	s_and_b32 s39, s38, 15
	s_lshl_b32 s40, s34, 6
	v_add_u32_e32 v4, s40, v47
	s_lshl_b32 s86, s39, 8
	v_add_u32_e32 v78, s40, v35
	v_add_u32_e32 v80, s40, v37
	v_add_u32_e32 v82, s40, v39
	v_ashrrev_i32_e32 v5, 31, v4
	v_ashrrev_i32_e32 v79, 31, v78
	v_ashrrev_i32_e32 v81, 31, v80
	v_ashrrev_i32_e32 v83, 31, v82
	v_lshl_add_u64 v[8:9], v[32:33], 0, s[86:87]
	v_lshlrev_b64 v[4:5], 12, v[4:5]
	v_lshlrev_b64 v[78:79], 12, v[78:79]
	v_lshlrev_b64 v[80:81], 12, v[80:81]
	v_lshlrev_b64 v[82:83], 12, v[82:83]
	v_lshl_add_u64 v[4:5], v[8:9], 0, v[4:5]
	v_lshl_add_u64 v[78:79], v[8:9], 0, v[78:79]
	v_lshl_add_u64 v[80:81], v[8:9], 0, v[80:81]
	v_lshl_add_u64 v[82:83], v[8:9], 0, v[82:83]
	global_load_dwordx4 v[4:7], v[4:5], off
	global_load_dwordx4 v[86:89], v[78:79], off
	global_load_dwordx4 v[90:93], v[80:81], off
	global_load_dwordx4 v[94:97], v[82:83], off
	v_add_u32_e32 v49, 0x4400, v41
	s_movk_i32 s34, 0x7f
	s_waitcnt vmcnt(3)
	ds_write_b128 v34, v[4:7]
	s_waitcnt vmcnt(2)
	ds_write_b128 v36, v[86:89]
	s_waitcnt vmcnt(1)
	ds_write_b128 v38, v[90:93]
	s_waitcnt vmcnt(0)
	ds_write_b128 v40, v[94:97]
	s_waitcnt lgkmcnt(0)
	s_barrier
	ds_read_b128 v[4:7], v44 offset:8704
	ds_read_b128 v[8:11], v44
	ds_read_b128 v[78:81], v44 offset:32
	s_waitcnt lgkmcnt(1)
	v_mfma_f32_32x32x16_bf16 v[16:31], v[8:11], v[0:3], 0
	ds_read_b128 v[82:85], v44 offset:8736
	v_mfma_f32_32x32x16_bf16 v[0:15], v[4:7], v[0:3], 0
	s_waitcnt lgkmcnt(1)
	v_mfma_f32_32x32x16_bf16 v[16:31], v[78:81], v[50:53], v[16:31]
	s_waitcnt lgkmcnt(0)
	v_mfma_f32_32x32x16_bf16 v[0:15], v[82:85], v[50:53], v[0:15]
	ds_read_b128 v[50:53], v44 offset:64
	ds_read_b128 v[78:81], v44 offset:8768
	s_waitcnt lgkmcnt(1)
	v_mfma_f32_32x32x16_bf16 v[16:31], v[50:53], v[54:57], v[16:31]
	s_waitcnt lgkmcnt(0)
	v_mfma_f32_32x32x16_bf16 v[0:15], v[78:81], v[54:57], v[0:15]
	ds_read_b128 v[50:53], v44 offset:96
	ds_read_b128 v[54:57], v44 offset:8800
	s_waitcnt lgkmcnt(1)
	v_mfma_f32_32x32x16_bf16 v[16:31], v[50:53], v[58:61], v[16:31]
	s_waitcnt lgkmcnt(0)
	v_mfma_f32_32x32x16_bf16 v[0:15], v[54:57], v[58:61], v[0:15]
	ds_read_b128 v[50:53], v44 offset:128
	ds_read_b128 v[54:57], v44 offset:8832
	s_waitcnt lgkmcnt(1)
	v_mfma_f32_32x32x16_bf16 v[16:31], v[50:53], v[62:65], v[16:31]
	s_waitcnt lgkmcnt(0)
	v_mfma_f32_32x32x16_bf16 v[0:15], v[54:57], v[62:65], v[0:15]
	ds_read_b128 v[50:53], v44 offset:160
	ds_read_b128 v[54:57], v44 offset:8864
	s_waitcnt lgkmcnt(1)
	v_mfma_f32_32x32x16_bf16 v[16:31], v[50:53], v[66:69], v[16:31]
	s_waitcnt lgkmcnt(0)
	v_mfma_f32_32x32x16_bf16 v[0:15], v[54:57], v[66:69], v[0:15]
	ds_read_b128 v[50:53], v44 offset:192
	ds_read_b128 v[54:57], v44 offset:8896
	s_waitcnt lgkmcnt(1)
	v_mfma_f32_32x32x16_bf16 v[16:31], v[50:53], v[70:73], v[16:31]
	s_waitcnt lgkmcnt(0)
	v_mfma_f32_32x32x16_bf16 v[0:15], v[54:57], v[70:73], v[0:15]
	ds_read_b128 v[50:53], v44 offset:224
	ds_read_b128 v[54:57], v44 offset:8928
	s_waitcnt lgkmcnt(1)
	v_mfma_f32_32x32x16_bf16 v[16:31], v[50:53], v[74:77], v[16:31]
	s_waitcnt lgkmcnt(0)
	v_mfma_f32_32x32x16_bf16 v[0:15], v[54:57], v[74:77], v[0:15]
	s_nop 9
	ds_write2_b32 v49, v16, v17 offset1:133
	v_add_u32_e32 v16, 0x4800, v41
	ds_write2_b32 v16, v18, v19 offset0:10 offset1:143
	v_add_u32_e32 v16, 0x5400, v41
	ds_write2_b32 v16, v20, v21 offset0:40 offset1:173
	v_add_u32_e32 v16, 0x5800, v41
	ds_write2_b32 v16, v22, v23 offset0:50 offset1:183
	v_add_u32_e32 v16, 0x6400, v41
	ds_write2_b32 v16, v24, v25 offset0:80 offset1:213
	v_add_u32_e32 v16, 0x6800, v41
	ds_write2_b32 v16, v26, v27 offset0:90 offset1:223
	v_add_u32_e32 v16, 0x7400, v41
	ds_write2_b32 v16, v28, v29 offset0:120 offset1:253
	v_add_u32_e32 v16, 0x7a00, v41
	ds_write2_b32 v16, v30, v31 offset0:2 offset1:135
	v_add_u32_e32 v16, 0x8600, v41
	ds_write2_b32 v16, v0, v1 offset0:32 offset1:165
	v_add_u32_e32 v0, 0x8a00, v41
	ds_write2_b32 v0, v2, v3 offset0:42 offset1:175
	v_add_u32_e32 v0, 0x9600, v41
	ds_write2_b32 v0, v4, v5 offset0:72 offset1:205
	v_add_u32_e32 v0, 0x9a00, v41
	ds_write2_b32 v0, v6, v7 offset0:82 offset1:215
	v_add_u32_e32 v0, 0xa600, v41
	ds_write2_b32 v0, v8, v9 offset0:112 offset1:245
	v_add_u32_e32 v0, 0xaa00, v41
	ds_write2_b32 v0, v10, v11 offset0:122 offset1:255
	v_add_u32_e32 v0, 0xb800, v41
	ds_write2_b32 v0, v12, v13 offset0:24 offset1:157
	v_add_u32_e32 v0, 0xbc00, v41
	ds_write2_b32 v0, v14, v15 offset0:34 offset1:167
	v_add_u32_e32 v0, 0x4400, v48
	s_waitcnt lgkmcnt(0)
	s_barrier
; DI void phase_topk(const Params& p, int l, int bid, int nblk, char* smem) {
;     ...
;       const int r = tid >> 2, part = tid & 3;
;       u32 key[32];
; #pragma unroll
;       for (int j = 0; j < 32; ++j) {
;         const u32 u = __float_as_uint(sc[r * 133 + part * 33 + j]);
;         const u32 ord = (u & 0x80000000u) ? ~u : (u | 0x80000000u);
;         key[j] = (ord & ~127u) | (u32)(127 - (part * 32 + j));
;       }
	ds_read2_b32 v[0:1], v0 offset1:1
	s_waitcnt lgkmcnt(0)
	v_not_b32_e32 v2, v0
	v_cmp_gt_i32_e32 vcc, 0, v0
	s_nop 1
	v_cndmask_b32_e64 v0, -|v0|, v2, vcc
	v_and_b32_e32 v0, 0xffffff80, v0
	v_bitop3_b32 v2, v0, s34, v46 bitop3:0x36
	v_not_b32_e32 v0, v1
	v_cmp_gt_i32_e32 vcc, 0, v1
	s_nop 1
	v_cndmask_b32_e64 v0, -|v1|, v0, vcc
	v_and_b32_e32 v0, 0xffffff80, v0
	v_sub_u32_e32 v0, v0, v46
	v_add_u32_e32 v3, 0x7e, v0
	v_add_u32_e32 v0, 0x4408, v48
	ds_read2_b32 v[0:1], v0 offset1:1
	s_waitcnt lgkmcnt(0)
	v_not_b32_e32 v4, v0
	v_cmp_gt_i32_e32 vcc, 0, v0
	s_nop 1
	v_cndmask_b32_e64 v0, -|v0|, v4, vcc
	v_and_b32_e32 v0, 0xffffff80, v0
	v_sub_u32_e32 v0, v0, v46
	v_add_u32_e32 v4, 0x7d, v0
	v_not_b32_e32 v0, v1
	v_cmp_gt_i32_e32 vcc, 0, v1
	s_nop 1
	v_cndmask_b32_e64 v0, -|v1|, v0, vcc
	v_and_b32_e32 v0, 0xffffff80, v0
	v_sub_u32_e32 v0, v0, v46
	v_add_u32_e32 v5, 0x7c, v0
	v_add_u32_e32 v0, 0x4410, v48
	ds_read2_b32 v[0:1], v0 offset1:1
	s_waitcnt lgkmcnt(0)
	v_not_b32_e32 v6, v0
	v_cmp_gt_i32_e32 vcc, 0, v0
	s_nop 1
	v_cndmask_b32_e64 v0, -|v0|, v6, vcc
	v_and_b32_e32 v0, 0xffffff80, v0
	v_sub_u32_e32 v0, v0, v46
	v_add_u32_e32 v6, 0x7b, v0
	v_not_b32_e32 v0, v1
	v_cmp_gt_i32_e32 vcc, 0, v1
	s_nop 1
	v_cndmask_b32_e64 v0, -|v1|, v0, vcc
	v_and_b32_e32 v0, 0xffffff80, v0
	v_sub_u32_e32 v0, v0, v46
	v_add_u32_e32 v7, 0x7a, v0
	v_add_u32_e32 v0, 0x4418, v48
	ds_read2_b32 v[0:1], v0 offset1:1
	s_waitcnt lgkmcnt(0)
	v_not_b32_e32 v8, v0
	v_cmp_gt_i32_e32 vcc, 0, v0
	s_nop 1
	v_cndmask_b32_e64 v0, -|v0|, v8, vcc
	v_and_b32_e32 v0, 0xffffff80, v0
	v_sub_u32_e32 v0, v0, v46
	v_add_u32_e32 v8, 0x79, v0
	v_not_b32_e32 v0, v1
	v_cmp_gt_i32_e32 vcc, 0, v1
	s_nop 1
	v_cndmask_b32_e64 v0, -|v1|, v0, vcc
	v_and_b32_e32 v0, 0xffffff80, v0
	v_sub_u32_e32 v0, v0, v46
	v_add_u32_e32 v9, 0x78, v0
	v_add_u32_e32 v0, 0x4420, v48
	ds_read2_b32 v[0:1], v0 offset1:1
	s_waitcnt lgkmcnt(0)
	v_not_b32_e32 v10, v0
	v_cmp_gt_i32_e32 vcc, 0, v0
	s_nop 1
	v_cndmask_b32_e64 v0, -|v0|, v10, vcc
	v_and_b32_e32 v0, 0xffffff80, v0
	v_sub_u32_e32 v0, v0, v46
	v_add_u32_e32 v10, 0x77, v0
	v_not_b32_e32 v0, v1
	v_cmp_gt_i32_e32 vcc, 0, v1
	s_nop 1
	v_cndmask_b32_e64 v0, -|v1|, v0, vcc
	v_and_b32_e32 v0, 0xffffff80, v0
	v_sub_u32_e32 v0, v0, v46
	v_add_u32_e32 v11, 0x76, v0
	v_add_u32_e32 v0, 0x4428, v48
	ds_read2_b32 v[0:1], v0 offset1:1
	s_waitcnt lgkmcnt(0)
	v_not_b32_e32 v12, v0
	v_cmp_gt_i32_e32 vcc, 0, v0
	s_nop 1
	v_cndmask_b32_e64 v0, -|v0|, v12, vcc
	v_and_b32_e32 v0, 0xffffff80, v0
	v_sub_u32_e32 v0, v0, v46
	v_add_u32_e32 v12, 0x75, v0
	v_not_b32_e32 v0, v1
	v_cmp_gt_i32_e32 vcc, 0, v1
	s_nop 1
	v_cndmask_b32_e64 v0, -|v1|, v0, vcc
	v_and_b32_e32 v0, 0xffffff80, v0
	v_sub_u32_e32 v0, v0, v46
	v_add_u32_e32 v13, 0x74, v0
	v_add_u32_e32 v0, 0x4430, v48
	ds_read2_b32 v[0:1], v0 offset1:1
	s_waitcnt lgkmcnt(0)
	v_not_b32_e32 v14, v0
	v_cmp_gt_i32_e32 vcc, 0, v0
	s_nop 1
	v_cndmask_b32_e64 v0, -|v0|, v14, vcc
	v_and_b32_e32 v0, 0xffffff80, v0
	v_sub_u32_e32 v0, v0, v46
	v_add_u32_e32 v14, 0x73, v0
	v_not_b32_e32 v0, v1
	v_cmp_gt_i32_e32 vcc, 0, v1
	s_nop 1
	v_cndmask_b32_e64 v0, -|v1|, v0, vcc
	v_and_b32_e32 v0, 0xffffff80, v0
	v_sub_u32_e32 v0, v0, v46
	v_add_u32_e32 v15, 0x72, v0
	v_add_u32_e32 v0, 0x4438, v48
	ds_read2_b32 v[0:1], v0 offset1:1
	s_waitcnt lgkmcnt(0)
	v_not_b32_e32 v16, v0
	v_cmp_gt_i32_e32 vcc, 0, v0
	s_nop 1
	v_cndmask_b32_e64 v0, -|v0|, v16, vcc
	v_not_b32_e32 v16, v1
	v_cmp_gt_i32_e32 vcc, 0, v1
	v_and_b32_e32 v0, 0xffffff80, v0
	v_sub_u32_e32 v0, v0, v46
	v_cndmask_b32_e64 v1, -|v1|, v16, vcc
	v_add_u32_e32 v16, 0x4440, v48
	ds_read2_b32 v[16:17], v16 offset1:1
	v_and_b32_e32 v1, 0xffffff80, v1
	v_sub_u32_e32 v1, v1, v46
	v_add_u32_e32 v0, 0x71, v0
	v_add_u32_e32 v1, 0x70, v1
	s_waitcnt lgkmcnt(0)
	v_not_b32_e32 v18, v16
	v_cmp_gt_i32_e32 vcc, 0, v16
	s_nop 1
	v_cndmask_b32_e64 v16, -|v16|, v18, vcc
	v_not_b32_e32 v18, v17
	v_cmp_gt_i32_e32 vcc, 0, v17
	v_and_b32_e32 v16, 0xffffff80, v16
	v_sub_u32_e32 v16, v16, v46
	v_cndmask_b32_e64 v17, -|v17|, v18, vcc
	v_add_u32_e32 v18, 0x4448, v48
	ds_read2_b32 v[18:19], v18 offset1:1
	v_and_b32_e32 v17, 0xffffff80, v17
	v_sub_u32_e32 v17, v17, v46
	v_add_u32_e32 v16, 0x6f, v16
	v_add_u32_e32 v17, 0x6e, v17
	s_waitcnt lgkmcnt(0)
	v_not_b32_e32 v20, v18
	v_cmp_gt_i32_e32 vcc, 0, v18
	s_nop 1
	v_cndmask_b32_e64 v18, -|v18|, v20, vcc
	v_not_b32_e32 v20, v19
	v_cmp_gt_i32_e32 vcc, 0, v19
	v_and_b32_e32 v18, 0xffffff80, v18
	v_sub_u32_e32 v18, v18, v46
	v_cndmask_b32_e64 v19, -|v19|, v20, vcc
	v_add_u32_e32 v20, 0x4450, v48
	ds_read2_b32 v[20:21], v20 offset1:1
	v_and_b32_e32 v19, 0xffffff80, v19
	v_sub_u32_e32 v19, v19, v46
	v_add_u32_e32 v18, 0x6d, v18
	v_add_u32_e32 v19, 0x6c, v19
	s_waitcnt lgkmcnt(0)
	v_not_b32_e32 v22, v20
	v_cmp_gt_i32_e32 vcc, 0, v20
	s_nop 1
	v_cndmask_b32_e64 v20, -|v20|, v22, vcc
	v_not_b32_e32 v22, v21
	v_cmp_gt_i32_e32 vcc, 0, v21
	v_and_b32_e32 v20, 0xffffff80, v20
	v_sub_u32_e32 v20, v20, v46
	v_cndmask_b32_e64 v21, -|v21|, v22, vcc
	v_add_u32_e32 v22, 0x4458, v48
	ds_read2_b32 v[22:23], v22 offset1:1
	v_and_b32_e32 v21, 0xffffff80, v21
	v_sub_u32_e32 v21, v21, v46
	v_add_u32_e32 v20, 0x6b, v20
	v_add_u32_e32 v21, 0x6a, v21
	s_waitcnt lgkmcnt(0)
	v_not_b32_e32 v24, v22
	v_cmp_gt_i32_e32 vcc, 0, v22
	s_nop 1
	v_cndmask_b32_e64 v22, -|v22|, v24, vcc
	v_and_b32_e32 v22, 0xffffff80, v22
	v_sub_u32_e32 v22, v22, v46
	v_add_u32_e32 v24, 0x69, v22
	v_not_b32_e32 v22, v23
	v_cmp_gt_i32_e32 vcc, 0, v23
	s_nop 1
	v_cndmask_b32_e64 v22, -|v23|, v22, vcc
	v_and_b32_e32 v22, 0xffffff80, v22
	v_sub_u32_e32 v22, v22, v46
	v_add_u32_e32 v25, 0x68, v22
	v_add_u32_e32 v22, 0x4460, v48
	ds_read2_b32 v[22:23], v22 offset1:1
	s_waitcnt lgkmcnt(0)
; DI void phase_topk(const Params& p, int l, int bid, int nblk, char* smem) {
;     ...
;       for (int j = 0; j < 32; ++j) {
;         const u32 u = __float_as_uint(sc[r * 133 + part * 33 + j]);
;         const u32 ord = (u & 0x80000000u) ? ~u : (u | 0x80000000u);
;         key[j] = (ord & ~127u) | (u32)(127 - (part * 32 + j));
;       }
;       float* tv = TV + ((size_t)(row0 + r) * 16 + hh) * 16;
;       int* ti = TI + ((size_t)(row0 + r) * 16 + hh) * 16;
; #pragma unroll
;       for (int k = 2; k <= 32; k <<= 1)
; #pragma unroll
;         for (int j = k >> 1; j > 0; j >>= 1)
; #pragma unroll
;           for (int i = 0; i < 32; ++i) {
;             const int l2 = i ^ j;
;             if (l2 > i) {
;               const u32 ka = key[i], kb2 = key[l2];
;               const u32 lo = ka < kb2 ? ka : kb2, hi = ka < kb2 ? kb2 : ka;
;               if ((i & k) == 0) { key[i] = lo; key[l2] = hi; } else { key[i] = hi; key[l2] = lo; }
;             }
;           }
	v_not_b32_e32 v26, v22
	v_cmp_gt_i32_e32 vcc, 0, v22
	s_nop 1
	v_cndmask_b32_e64 v22, -|v22|, v26, vcc
	v_and_b32_e32 v22, 0xffffff80, v22
	v_sub_u32_e32 v22, v22, v46
	v_add_u32_e32 v26, 0x67, v22
	v_not_b32_e32 v22, v23
	v_cmp_gt_i32_e32 vcc, 0, v23
	s_nop 1
	v_cndmask_b32_e64 v22, -|v23|, v22, vcc
	v_and_b32_e32 v22, 0xffffff80, v22
	v_sub_u32_e32 v22, v22, v46
	v_add_u32_e32 v27, 0x66, v22
	v_add_u32_e32 v22, 0x4468, v48
	ds_read2_b32 v[22:23], v22 offset1:1
	s_waitcnt lgkmcnt(0)
	v_not_b32_e32 v28, v22
	v_cmp_gt_i32_e32 vcc, 0, v22
	s_nop 1
	v_cndmask_b32_e64 v22, -|v22|, v28, vcc
	v_and_b32_e32 v22, 0xffffff80, v22
	v_sub_u32_e32 v22, v22, v46
	v_add_u32_e32 v28, 0x65, v22
	v_not_b32_e32 v22, v23
	v_cmp_gt_i32_e32 vcc, 0, v23
	s_nop 1
	v_cndmask_b32_e64 v22, -|v23|, v22, vcc
	v_and_b32_e32 v22, 0xffffff80, v22
	v_sub_u32_e32 v22, v22, v46
	v_add_u32_e32 v29, 0x64, v22
	v_add_u32_e32 v22, 0x4470, v48
	ds_read2_b32 v[22:23], v22 offset1:1
	s_waitcnt lgkmcnt(0)
	v_not_b32_e32 v30, v22
	v_cmp_gt_i32_e32 vcc, 0, v22
	s_nop 1
	v_cndmask_b32_e64 v22, -|v22|, v30, vcc
	v_and_b32_e32 v22, 0xffffff80, v22
	v_sub_u32_e32 v22, v22, v46
	v_add_u32_e32 v30, 0x63, v22
	v_not_b32_e32 v22, v23
	v_cmp_gt_i32_e32 vcc, 0, v23
	s_nop 1
	v_cndmask_b32_e64 v22, -|v23|, v22, vcc
	v_and_b32_e32 v22, 0xffffff80, v22
	v_sub_u32_e32 v22, v22, v46
	v_add_u32_e32 v31, 0x62, v22
	v_add_u32_e32 v22, 0x4478, v48
	ds_read2_b32 v[22:23], v22 offset1:1
	s_waitcnt lgkmcnt(0)
	v_not_b32_e32 v49, v22
	v_cmp_gt_i32_e32 vcc, 0, v22
	s_nop 1
	v_cndmask_b32_e64 v22, -|v22|, v49, vcc
	v_not_b32_e32 v49, v23
	v_cmp_gt_i32_e32 vcc, 0, v23
	v_and_b32_e32 v22, 0xffffff80, v22
	v_sub_u32_e32 v22, v22, v46
	v_cndmask_b32_e64 v23, -|v23|, v49, vcc
	v_and_b32_e32 v23, 0xffffff80, v23
	v_sub_u32_e32 v23, v23, v46
	v_add_u32_e32 v22, 0x61, v22
	v_add_u32_e32 v23, 0x60, v23
	v_min_u32_e32 v49, v2, v3
	v_max_u32_e32 v2, v2, v3
	v_min_u32_e32 v3, v4, v5
	v_max_u32_e32 v4, v4, v5
	v_min_u32_e32 v5, v6, v7
	v_max_u32_e32 v6, v6, v7
	v_min_u32_e32 v7, v8, v9
	v_max_u32_e32 v8, v8, v9
	v_min_u32_e32 v9, v10, v11
	v_max_u32_e32 v10, v10, v11
	v_min_u32_e32 v11, v12, v13
	v_max_u32_e32 v12, v12, v13
	v_min_u32_e32 v13, v14, v15
	v_max_u32_e32 v14, v14, v15
	v_min_u32_e32 v15, v0, v1
	v_max_u32_e32 v0, v0, v1
	v_min_u32_e32 v1, v16, v17
	v_max_u32_e32 v16, v16, v17
	v_min_u32_e32 v17, v18, v19
	v_max_u32_e32 v18, v18, v19
	v_min_u32_e32 v19, v20, v21
	v_max_u32_e32 v20, v20, v21
	v_min_u32_e32 v21, v24, v25
	v_max_u32_e32 v24, v24, v25
	v_min_u32_e32 v25, v26, v27
	v_max_u32_e32 v26, v26, v27
	v_min_u32_e32 v27, v28, v29
	v_max_u32_e32 v28, v28, v29
	v_min_u32_e32 v29, v30, v31
	v_max_u32_e32 v30, v30, v31
	v_min_u32_e32 v31, v22, v23
	v_max_u32_e32 v22, v22, v23
	v_min_u32_e32 v23, v49, v4
	v_max_u32_e32 v4, v49, v4
	v_min_u32_e32 v49, v2, v3
	v_max_u32_e32 v2, v2, v3
	v_min_u32_e32 v3, v5, v8
	v_max_u32_e32 v5, v5, v8
	v_min_u32_e32 v8, v6, v7
	v_max_u32_e32 v6, v6, v7
	v_min_u32_e32 v7, v9, v12
	v_max_u32_e32 v9, v9, v12
	v_min_u32_e32 v12, v10, v11
	v_max_u32_e32 v10, v10, v11
	v_min_u32_e32 v11, v13, v0
	v_max_u32_e32 v0, v13, v0
	v_min_u32_e32 v13, v14, v15
	v_max_u32_e32 v14, v14, v15
	v_min_u32_e32 v15, v1, v18
	v_max_u32_e32 v1, v1, v18
	v_min_u32_e32 v18, v16, v17
	v_max_u32_e32 v16, v16, v17
	v_min_u32_e32 v17, v19, v24
	v_max_u32_e32 v19, v19, v24
	v_min_u32_e32 v24, v20, v21
	v_max_u32_e32 v20, v20, v21
	v_min_u32_e32 v21, v25, v28
	v_max_u32_e32 v25, v25, v28
	v_min_u32_e32 v28, v26, v27
	v_max_u32_e32 v26, v26, v27
	v_min_u32_e32 v27, v29, v22
	v_max_u32_e32 v22, v29, v22
	v_min_u32_e32 v29, v30, v31
	v_max_u32_e32 v30, v30, v31
	v_min_u32_e32 v31, v23, v49
	v_max_u32_e32 v23, v23, v49
	v_min_u32_e32 v49, v4, v2
	v_max_u32_e32 v2, v4, v2
	v_min_u32_e32 v4, v5, v6
	v_max_u32_e32 v5, v5, v6
	v_min_u32_e32 v6, v3, v8
	v_max_u32_e32 v3, v3, v8
	v_min_u32_e32 v8, v7, v12
	v_max_u32_e32 v7, v7, v12
	v_min_u32_e32 v12, v9, v10
	v_max_u32_e32 v9, v9, v10
	v_min_u32_e32 v10, v0, v14
	v_max_u32_e32 v0, v0, v14
	v_min_u32_e32 v14, v11, v13
	v_max_u32_e32 v11, v11, v13
	v_min_u32_e32 v13, v15, v18
	v_max_u32_e32 v15, v15, v18
	v_min_u32_e32 v18, v1, v16
	v_max_u32_e32 v1, v1, v16
	v_min_u32_e32 v16, v19, v20
	v_max_u32_e32 v19, v19, v20
	v_min_u32_e32 v20, v17, v24
	v_max_u32_e32 v17, v17, v24
	v_min_u32_e32 v24, v21, v28
	v_max_u32_e32 v21, v21, v28
	v_min_u32_e32 v28, v25, v26
	v_max_u32_e32 v25, v25, v26
	v_min_u32_e32 v26, v22, v30
	v_max_u32_e32 v22, v22, v30
	v_min_u32_e32 v30, v27, v29
	v_max_u32_e32 v27, v27, v29
	v_min_u32_e32 v29, v31, v5
	v_max_u32_e32 v5, v31, v5
	v_min_u32_e32 v31, v23, v4
	v_max_u32_e32 v4, v23, v4
	v_min_u32_e32 v23, v49, v3
	v_max_u32_e32 v3, v49, v3
	v_min_u32_e32 v49, v2, v6
	v_max_u32_e32 v2, v2, v6
	v_min_u32_e32 v6, v8, v0
	v_max_u32_e32 v0, v8, v0
	v_min_u32_e32 v8, v7, v10
	v_max_u32_e32 v7, v7, v10
	v_min_u32_e32 v10, v12, v11
	v_max_u32_e32 v11, v12, v11
	v_min_u32_e32 v12, v9, v14
	v_max_u32_e32 v9, v9, v14
	v_min_u32_e32 v14, v13, v19
	v_max_u32_e32 v13, v13, v19
	v_min_u32_e32 v19, v15, v16
	v_max_u32_e32 v15, v15, v16
	v_min_u32_e32 v16, v18, v17
	v_max_u32_e32 v17, v18, v17
	v_min_u32_e32 v18, v1, v20
	v_max_u32_e32 v1, v1, v20
	v_min_u32_e32 v20, v24, v22
	v_max_u32_e32 v22, v24, v22
	v_min_u32_e32 v24, v21, v26
	v_max_u32_e32 v21, v21, v26
	v_min_u32_e32 v26, v28, v27
	v_max_u32_e32 v27, v28, v27
	v_min_u32_e32 v28, v25, v30
	v_max_u32_e32 v25, v25, v30
	v_min_u32_e32 v30, v29, v23
	v_max_u32_e32 v23, v29, v23
	v_min_u32_e32 v29, v31, v49
	v_max_u32_e32 v31, v31, v49
	v_min_u32_e32 v49, v5, v3
	v_max_u32_e32 v3, v5, v3
	v_min_u32_e32 v5, v4, v2
; DI void phase_topk(const Params& p, int l, int bid, int nblk, char* smem) {
;     ...
; #pragma unroll
;       for (int k = 2; k <= 32; k <<= 1)
; #pragma unroll
;         for (int j = k >> 1; j > 0; j >>= 1)
; #pragma unroll
;           for (int i = 0; i < 32; ++i) {
;             const int l2 = i ^ j;
;             if (l2 > i) {
;               const u32 ka = key[i], kb2 = key[l2];
;               const u32 lo = ka < kb2 ? ka : kb2, hi = ka < kb2 ? kb2 : ka;
;               if ((i & k) == 0) { key[i] = lo; key[l2] = hi; } else { key[i] = hi; key[l2] = lo; }
;             }
;           }
;       u32 T[16];
; #pragma unroll
;       for (int t = 0; t < 16; ++t) T[t] = key[31 - t];
	v_max_u32_e32 v2, v4, v2
	v_min_u32_e32 v4, v0, v11
	v_max_u32_e32 v0, v0, v11
	v_min_u32_e32 v11, v7, v9
	v_max_u32_e32 v7, v7, v9
	v_min_u32_e32 v9, v6, v10
	v_max_u32_e32 v6, v6, v10
	v_min_u32_e32 v10, v8, v12
	v_max_u32_e32 v8, v8, v12
	v_min_u32_e32 v12, v14, v16
	v_max_u32_e32 v14, v14, v16
	v_min_u32_e32 v16, v19, v18
	v_max_u32_e32 v18, v19, v18
	v_min_u32_e32 v19, v13, v17
	v_max_u32_e32 v13, v13, v17
	v_min_u32_e32 v17, v15, v1
	v_max_u32_e32 v1, v15, v1
	v_min_u32_e32 v15, v22, v27
	v_max_u32_e32 v22, v22, v27
	v_min_u32_e32 v27, v21, v25
	v_max_u32_e32 v21, v21, v25
	v_min_u32_e32 v25, v20, v26
	v_max_u32_e32 v20, v20, v26
	v_min_u32_e32 v26, v24, v28
	v_max_u32_e32 v24, v24, v28
	v_min_u32_e32 v28, v30, v29
	v_max_u32_e32 v29, v30, v29
	v_min_u32_e32 v30, v23, v31
	v_max_u32_e32 v23, v23, v31
	v_min_u32_e32 v31, v49, v5
	v_max_u32_e32 v5, v49, v5
	v_min_u32_e32 v49, v3, v2
	v_max_u32_e32 v2, v3, v2
	v_min_u32_e32 v3, v0, v7
	v_max_u32_e32 v0, v0, v7
	v_min_u32_e32 v7, v4, v11
	v_max_u32_e32 v4, v4, v11
	v_min_u32_e32 v11, v6, v8
	v_max_u32_e32 v6, v6, v8
	v_min_u32_e32 v8, v9, v10
	v_max_u32_e32 v9, v9, v10
	v_min_u32_e32 v10, v12, v16
	v_max_u32_e32 v12, v12, v16
	v_min_u32_e32 v16, v14, v18
	v_max_u32_e32 v14, v14, v18
	v_min_u32_e32 v18, v19, v17
	v_max_u32_e32 v17, v19, v17
	v_min_u32_e32 v19, v13, v1
	v_max_u32_e32 v1, v13, v1
	v_min_u32_e32 v13, v22, v21
	v_max_u32_e32 v21, v22, v21
	v_min_u32_e32 v22, v15, v27
	v_max_u32_e32 v15, v15, v27
	v_min_u32_e32 v27, v20, v24
	v_max_u32_e32 v20, v20, v24
	v_min_u32_e32 v24, v25, v26
	v_max_u32_e32 v25, v25, v26
	v_min_u32_e32 v26, v28, v0
	v_max_u32_e32 v0, v28, v0
	v_min_u32_e32 v28, v29, v3
	v_max_u32_e32 v3, v29, v3
	v_min_u32_e32 v29, v30, v4
	v_max_u32_e32 v4, v30, v4
	v_min_u32_e32 v30, v23, v7
	v_max_u32_e32 v7, v23, v7
	v_min_u32_e32 v23, v31, v6
	v_max_u32_e32 v6, v31, v6
	v_min_u32_e32 v31, v5, v11
	v_max_u32_e32 v5, v5, v11
	v_min_u32_e32 v11, v49, v9
	v_max_u32_e32 v9, v49, v9
	v_min_u32_e32 v49, v2, v8
	v_max_u32_e32 v2, v2, v8
	v_min_u32_e32 v8, v10, v21
	v_max_u32_e32 v10, v10, v21
	v_min_u32_e32 v21, v12, v13
	v_max_u32_e32 v12, v12, v13
	v_min_u32_e32 v13, v16, v15
	v_max_u32_e32 v15, v16, v15
	v_min_u32_e32 v16, v14, v22
	v_max_u32_e32 v14, v14, v22
	v_min_u32_e32 v22, v18, v20
	v_max_u32_e32 v18, v18, v20
	v_min_u32_e32 v20, v17, v27
	v_max_u32_e32 v17, v17, v27
	v_min_u32_e32 v27, v19, v25
	v_max_u32_e32 v19, v19, v25
	v_min_u32_e32 v25, v1, v24
	v_max_u32_e32 v1, v1, v24
	v_min_u32_e32 v24, v26, v23
	v_max_u32_e32 v23, v26, v23
	v_min_u32_e32 v26, v28, v31
	v_max_u32_e32 v28, v28, v31
	v_min_u32_e32 v31, v29, v11
	v_max_u32_e32 v11, v29, v11
	v_min_u32_e32 v29, v30, v49
	v_max_u32_e32 v30, v30, v49
	v_min_u32_e32 v49, v0, v6
	v_max_u32_e32 v0, v0, v6
	v_min_u32_e32 v6, v3, v5
	v_max_u32_e32 v3, v3, v5
	v_min_u32_e32 v5, v4, v9
	v_max_u32_e32 v4, v4, v9
	v_min_u32_e32 v9, v7, v2
	v_max_u32_e32 v2, v7, v2
	v_min_u32_e32 v7, v10, v18
	v_max_u32_e32 v10, v10, v18
	v_min_u32_e32 v18, v12, v17
	v_max_u32_e32 v12, v12, v17
	v_min_u32_e32 v17, v15, v19
	v_max_u32_e32 v15, v15, v19
	v_min_u32_e32 v19, v14, v1
	v_max_u32_e32 v1, v14, v1
	v_min_u32_e32 v14, v8, v22
	v_max_u32_e32 v8, v8, v22
	v_min_u32_e32 v22, v21, v20
	v_max_u32_e32 v20, v21, v20
	v_min_u32_e32 v21, v13, v27
	v_max_u32_e32 v13, v13, v27
	v_min_u32_e32 v27, v16, v25
	v_max_u32_e32 v16, v16, v25
	v_min_u32_e32 v25, v24, v31
	v_max_u32_e32 v24, v24, v31
	v_min_u32_e32 v31, v26, v29
	v_max_u32_e32 v26, v26, v29
	v_min_u32_e32 v29, v23, v11
	v_max_u32_e32 v11, v23, v11
	v_min_u32_e32 v23, v28, v30
	v_max_u32_e32 v28, v28, v30
	v_min_u32_e32 v30, v49, v5
	v_max_u32_e32 v5, v49, v5
	v_min_u32_e32 v49, v6, v9
	v_max_u32_e32 v6, v6, v9
	v_min_u32_e32 v9, v0, v4
	v_max_u32_e32 v0, v0, v4
	v_min_u32_e32 v4, v3, v2
	v_max_u32_e32 v2, v3, v2
	v_min_u32_e32 v3, v10, v15
	v_max_u32_e32 v10, v10, v15
	v_min_u32_e32 v15, v12, v1
	v_max_u32_e32 v1, v12, v1
	v_min_u32_e32 v12, v7, v17
	v_max_u32_e32 v7, v7, v17
	v_min_u32_e32 v17, v18, v19
	v_max_u32_e32 v18, v18, v19
	v_min_u32_e32 v19, v8, v13
	v_max_u32_e32 v8, v8, v13
	v_min_u32_e32 v13, v20, v16
	v_max_u32_e32 v16, v20, v16
	v_min_u32_e32 v20, v14, v21
	v_max_u32_e32 v14, v14, v21
	v_min_u32_e32 v21, v22, v27
	v_max_u32_e32 v22, v22, v27
	v_min_u32_e32 v27, v25, v31
	v_min_u32_e32 v50, v24, v26
	v_min_u32_e32 v51, v29, v23
	v_min_u32_e32 v52, v11, v28
	v_min_u32_e32 v53, v30, v49
	v_min_u32_e32 v54, v5, v6
	v_min_u32_e32 v55, v9, v4
	v_min_u32_e32 v56, v0, v2
	v_min_u32_e32 v57, v10, v1
	v_min_u32_e32 v58, v3, v15
	v_min_u32_e32 v59, v7, v18
	v_min_u32_e32 v60, v12, v17
	v_min_u32_e32 v61, v8, v16
	v_min_u32_e32 v62, v19, v13
	v_min_u32_e32 v63, v14, v22
	v_min_u32_e32 v64, v20, v21
	v_max3_u32 v1, v27, v10, v1
	v_max3_u32 v10, v25, v31, v57
	v_max3_u32 v3, v50, v3, v15
	v_max3_u32 v15, v24, v26, v58
	v_max3_u32 v7, v51, v7, v18
	v_max3_u32 v18, v29, v23, v59
	v_max3_u32 v12, v52, v12, v17
	v_max3_u32 v11, v11, v28, v60
	v_max3_u32 v8, v53, v8, v16
	v_max3_u32 v16, v30, v49, v61
	v_max3_u32 v13, v54, v19, v13
	v_max3_u32 v5, v5, v6, v62
	v_max3_u32 v6, v55, v14, v22
	v_max3_u32 v4, v9, v4, v63
	v_max3_u32 v9, v56, v20, v21
	v_max3_u32 v0, v0, v2, v64
	v_min_u32_e32 v2, v1, v8
	v_max_u32_e32 v1, v1, v8
	v_min_u32_e32 v8, v10, v16
	v_max_u32_e32 v10, v10, v16
	v_min_u32_e32 v14, v3, v13
	v_max_u32_e32 v3, v3, v13
	v_min_u32_e32 v13, v15, v5
	v_max_u32_e32 v5, v15, v5
	v_min_u32_e32 v15, v7, v6
	v_max_u32_e32 v6, v7, v6
	v_min_u32_e32 v7, v18, v4
	v_min_u32_e32 v16, v12, v9
	v_max_u32_e32 v9, v12, v9
	v_min_u32_e32 v12, v11, v0
	v_max_u32_e32 v4, v18, v4
; DI void phase_topk(const Params& p, int l, int bid, int nblk, char* smem) {
;     ...
;       u32 T[16];
; #pragma unroll
;       for (int t = 0; t < 16; ++t) T[t] = key[31 - t];
;     ...
;       TOPK_MERGE(DPP_XOR1)
;       TOPK_MERGE(DPP_XOR2)
;     ...
;       if (part == 0) {
	v_max_u32_e32 v0, v11, v0
	v_min_u32_e32 v11, v2, v15
	v_max_u32_e32 v2, v2, v15
	v_min_u32_e32 v15, v8, v7
	v_max_u32_e32 v7, v8, v7
	v_min_u32_e32 v8, v14, v16
	v_max_u32_e32 v14, v14, v16
	v_min_u32_e32 v16, v13, v12
	v_max_u32_e32 v12, v13, v12
	v_min_u32_e32 v13, v1, v6
	v_max_u32_e32 v1, v1, v6
	v_min_u32_e32 v6, v10, v4
	v_max_u32_e32 v4, v10, v4
	v_min_u32_e32 v10, v3, v9
	v_max_u32_e32 v3, v3, v9
	v_min_u32_e32 v9, v5, v0
	v_max_u32_e32 v0, v5, v0
	v_min_u32_e32 v5, v11, v8
	v_max_u32_e32 v8, v11, v8
	v_min_u32_e32 v11, v15, v16
	v_max_u32_e32 v15, v15, v16
	v_min_u32_e32 v16, v2, v14
	v_max_u32_e32 v2, v2, v14
	v_min_u32_e32 v14, v7, v12
	v_max_u32_e32 v7, v7, v12
	v_min_u32_e32 v12, v13, v10
	v_max_u32_e32 v10, v13, v10
	v_min_u32_e32 v13, v6, v9
	v_max_u32_e32 v6, v6, v9
	v_min_u32_e32 v9, v1, v3
	v_max_u32_e32 v1, v1, v3
	v_min_u32_e32 v3, v4, v0
	v_max_u32_e32 v0, v4, v0
	v_min_u32_e32 v4, v5, v11
	v_max_u32_e32 v5, v5, v11
	v_min_u32_e32 v11, v8, v15
	v_max_u32_e32 v8, v8, v15
	v_min_u32_e32 v15, v16, v14
	v_max_u32_e32 v14, v16, v14
	v_min_u32_e32 v16, v2, v7
	v_max_u32_e32 v2, v2, v7
	v_min_u32_e32 v7, v12, v13
	v_max_u32_e32 v12, v12, v13
	v_min_u32_e32 v13, v10, v6
	v_max_u32_e32 v6, v10, v6
	v_min_u32_e32 v10, v9, v3
	v_max_u32_e32 v3, v9, v3
	v_min_u32_e32 v9, v1, v0
	v_max_u32_e32 v0, v1, v0
	v_mov_b32_dpp v1, v4 quad_perm:[1,0,3,2] row_mask:0xf bank_mask:0xf bound_ctrl:1
	v_max_u32_dpp v17, v5, v9 quad_perm:[1,0,3,2] row_mask:0xf bank_mask:0xf bound_ctrl:1
	v_max_u32_dpp v18, v11, v3 quad_perm:[1,0,3,2] row_mask:0xf bank_mask:0xf bound_ctrl:1
	v_max_u32_dpp v19, v8, v10 quad_perm:[1,0,3,2] row_mask:0xf bank_mask:0xf bound_ctrl:1
	v_max_u32_dpp v20, v15, v6 quad_perm:[1,0,3,2] row_mask:0xf bank_mask:0xf bound_ctrl:1
	v_max_u32_dpp v21, v14, v13 quad_perm:[1,0,3,2] row_mask:0xf bank_mask:0xf bound_ctrl:1
	v_max_u32_dpp v22, v16, v12 quad_perm:[1,0,3,2] row_mask:0xf bank_mask:0xf bound_ctrl:1
	v_max_u32_dpp v23, v2, v7 quad_perm:[1,0,3,2] row_mask:0xf bank_mask:0xf bound_ctrl:1
	v_max_u32_dpp v12, v12, v16 quad_perm:[1,0,3,2] row_mask:0xf bank_mask:0xf bound_ctrl:1
	v_max_u32_dpp v13, v13, v14 quad_perm:[1,0,3,2] row_mask:0xf bank_mask:0xf bound_ctrl:1
	v_max_u32_dpp v6, v6, v15 quad_perm:[1,0,3,2] row_mask:0xf bank_mask:0xf bound_ctrl:1
	v_max_u32_dpp v8, v10, v8 quad_perm:[1,0,3,2] row_mask:0xf bank_mask:0xf bound_ctrl:1
	v_max_u32_dpp v3, v3, v11 quad_perm:[1,0,3,2] row_mask:0xf bank_mask:0xf bound_ctrl:1
	v_max_u32_dpp v5, v9, v5 quad_perm:[1,0,3,2] row_mask:0xf bank_mask:0xf bound_ctrl:1
	v_max_u32_dpp v4, v0, v4 quad_perm:[1,0,3,2] row_mask:0xf bank_mask:0xf bound_ctrl:1
	v_max_u32_dpp v2, v7, v2 quad_perm:[1,0,3,2] row_mask:0xf bank_mask:0xf bound_ctrl:1
	v_max_u32_e32 v0, v0, v1
	v_max_u32_e32 v1, v0, v2
	v_min_u32_e32 v0, v0, v2
	v_max_u32_e32 v2, v17, v12
	v_min_u32_e32 v7, v17, v12
	v_max_u32_e32 v9, v18, v13
	v_min_u32_e32 v10, v18, v13
	v_max_u32_e32 v11, v19, v6
	v_min_u32_e32 v6, v19, v6
	v_max_u32_e32 v12, v20, v8
	v_min_u32_e32 v8, v20, v8
	v_max_u32_e32 v13, v21, v3
	v_min_u32_e32 v3, v21, v3
	v_max_u32_e32 v14, v22, v5
	v_min_u32_e32 v5, v22, v5
	v_max_u32_e32 v15, v23, v4
	v_min_u32_e32 v4, v23, v4
	v_max_u32_e32 v16, v1, v12
	v_min_u32_e32 v1, v1, v12
	v_max_u32_e32 v12, v2, v13
	v_min_u32_e32 v2, v2, v13
	v_max_u32_e32 v13, v9, v14
	v_min_u32_e32 v9, v9, v14
	v_max_u32_e32 v14, v11, v15
	v_min_u32_e32 v11, v11, v15
	v_max_u32_e32 v15, v0, v8
	v_min_u32_e32 v0, v0, v8
	v_max_u32_e32 v8, v7, v3
	v_min_u32_e32 v3, v7, v3
	v_max_u32_e32 v7, v10, v5
	v_min_u32_e32 v5, v10, v5
	v_max_u32_e32 v10, v6, v4
	v_min_u32_e32 v4, v6, v4
	v_max_u32_e32 v6, v16, v13
	v_min_u32_e32 v13, v16, v13
	v_max_u32_e32 v16, v12, v14
	v_min_u32_e32 v14, v12, v14
	v_max_u32_e32 v17, v1, v9
	v_min_u32_e32 v1, v1, v9
	v_max_u32_e32 v9, v2, v11
	v_min_u32_e32 v11, v2, v11
	v_max_u32_e32 v18, v15, v7
	v_min_u32_e32 v7, v15, v7
	v_max_u32_e32 v15, v8, v10
	v_min_u32_e32 v10, v8, v10
	v_max_u32_e32 v19, v0, v5
	v_min_u32_e32 v5, v0, v5
	v_max_u32_e32 v22, v3, v4
	v_min_u32_e32 v23, v3, v4
	v_max_u32_e32 v12, v6, v16
	v_min_u32_e32 v2, v6, v16
	v_max_u32_e32 v8, v13, v14
	v_min_u32_e32 v0, v13, v14
	v_max_u32_e32 v13, v17, v9
	v_min_u32_e32 v3, v17, v9
	v_max_u32_e32 v9, v1, v11
	v_min_u32_e32 v1, v1, v11
	v_max_u32_e32 v20, v18, v15
	v_min_u32_e32 v6, v18, v15
	v_max_u32_e32 v14, v7, v10
	v_min_u32_e32 v4, v7, v10
	v_max_u32_e32 v21, v19, v22
	v_min_u32_e32 v7, v19, v22
	v_max_u32_e32 v16, v5, v23
	v_min_u32_e32 v5, v5, v23
	v_mov_b32_dpp v24, v7 quad_perm:[2,3,0,1] row_mask:0xf bank_mask:0xf bound_ctrl:1
	v_mov_b32_dpp v15, v16 quad_perm:[2,3,0,1] row_mask:0xf bank_mask:0xf bound_ctrl:1
	v_mov_b32_dpp v26, v5 quad_perm:[2,3,0,1] row_mask:0xf bank_mask:0xf bound_ctrl:1
	v_mov_b32_dpp v10, v21 quad_perm:[2,3,0,1] row_mask:0xf bank_mask:0xf bound_ctrl:1
	v_mov_b32_dpp v27, v4 quad_perm:[2,3,0,1] row_mask:0xf bank_mask:0xf bound_ctrl:1
	v_mov_b32_dpp v17, v14 quad_perm:[2,3,0,1] row_mask:0xf bank_mask:0xf bound_ctrl:1
	v_mov_b32_dpp v25, v6 quad_perm:[2,3,0,1] row_mask:0xf bank_mask:0xf bound_ctrl:1
	v_mov_b32_dpp v11, v20 quad_perm:[2,3,0,1] row_mask:0xf bank_mask:0xf bound_ctrl:1
	v_mov_b32_dpp v30, v1 quad_perm:[2,3,0,1] row_mask:0xf bank_mask:0xf bound_ctrl:1
	v_mov_b32_dpp v22, v9 quad_perm:[2,3,0,1] row_mask:0xf bank_mask:0xf bound_ctrl:1
	v_mov_b32_dpp v28, v3 quad_perm:[2,3,0,1] row_mask:0xf bank_mask:0xf bound_ctrl:1
	v_mov_b32_dpp v18, v13 quad_perm:[2,3,0,1] row_mask:0xf bank_mask:0xf bound_ctrl:1
	v_mov_b32_dpp v31, v0 quad_perm:[2,3,0,1] row_mask:0xf bank_mask:0xf bound_ctrl:1
	v_mov_b32_dpp v23, v8 quad_perm:[2,3,0,1] row_mask:0xf bank_mask:0xf bound_ctrl:1
	v_mov_b32_dpp v29, v2 quad_perm:[2,3,0,1] row_mask:0xf bank_mask:0xf bound_ctrl:1
	v_mov_b32_dpp v19, v12 quad_perm:[2,3,0,1] row_mask:0xf bank_mask:0xf bound_ctrl:1
	s_and_saveexec_b64 s[34:35], s[0:1]
	s_cbranch_execz .LBB0_1447
; DI void phase_topk(const Params& p, int l, int bid, int nblk, char* smem) {
;     ...
;       if (part == 0) {
;         float ov[16];
;         int oi[16];
; #pragma unroll
;         for (int rd = 0; rd < 16; ++rd) {
;           const u32 best = T[rd];
;           const u32 ordv = best & ~127u;
;           const u32 uu = (ordv & 0x80000000u) ? (ordv & 0x7FFFFFFFu) : ~ordv;
;           ov[rd] = __uint_as_float(uu);
;           oi[rd] = 127 - (int)(best & 127u);
;         }
; #pragma unroll
;         for (int q = 0; q < 4; ++q) {
;           float4 fv = {ov[q * 4 + 0], ov[q * 4 + 1], ov[q * 4 + 2], ov[q * 4 + 3]};
;           int4 iv = {oi[q * 4 + 0], oi[q * 4 + 1], oi[q * 4 + 2], oi[q * 4 + 3]};
;           *(float4*)(tv + q * 4) = fv;
;           *(int4*)(ti + q * 4) = iv;
;         }
;       }
;     }
;     __syncthreads();
	v_max_u32_e32 v12, v12, v26
	v_max_u32_e32 v20, v20, v30
	v_max_u32_e32 v13, v13, v27
	v_max_u32_e32 v21, v21, v31
	v_max_u32_e32 v8, v8, v24
	v_max_u32_e32 v14, v14, v28
	v_max_u32_e32 v9, v9, v25
	v_max_u32_e32 v16, v16, v29
	v_max_u32_e32 v2, v2, v15
	v_max_u32_e32 v6, v6, v22
	v_max_u32_e32 v3, v3, v17
	v_max_u32_e32 v7, v7, v23
	v_max_u32_e32 v0, v0, v10
	v_max_u32_e32 v4, v4, v18
	v_max_u32_e32 v1, v1, v11
	v_max_u32_e32 v5, v5, v19
	v_min_u32_e32 v26, v12, v20
	v_min_u32_e32 v27, v13, v21
	v_min_u32_e32 v24, v8, v14
	v_min_u32_e32 v25, v9, v16
	v_min_u32_e32 v15, v2, v6
	v_min_u32_e32 v17, v3, v7
	v_min_u32_e32 v10, v0, v4
	v_min_u32_e32 v11, v1, v5
	v_max_u32_e32 v12, v12, v20
	v_max_u32_e32 v13, v13, v21
	v_max_u32_e32 v8, v8, v14
	v_max_u32_e32 v9, v9, v16
	v_max_u32_e32 v2, v2, v6
	v_max_u32_e32 v3, v3, v7
	v_max_u32_e32 v0, v0, v4
	v_max_u32_e32 v1, v1, v5
	v_min_u32_e32 v20, v12, v13
	v_min_u32_e32 v14, v8, v9
	v_min_u32_e32 v6, v2, v3
	v_min_u32_e32 v4, v0, v1
	v_min_u32_e32 v16, v20, v14
	v_min_u32_e32 v5, v6, v4
	v_min_u32_e32 v21, v16, v5
	v_max_u32_e32 v16, v16, v5
	v_max_u32_e32 v5, v20, v14
	v_max_u32_e32 v4, v6, v4
	v_min_u32_e32 v14, v5, v4
	v_max_u32_e32 v20, v5, v4
	v_max_u32_e32 v4, v12, v13
	v_max_u32_e32 v5, v8, v9
	v_max_u32_e32 v2, v2, v3
	v_max_u32_e32 v0, v0, v1
	v_min_u32_e32 v6, v4, v5
	v_min_u32_e32 v1, v2, v0
	v_min_u32_e32 v3, v6, v1
	v_max_u32_e32 v8, v6, v1
	v_max_u32_e32 v1, v4, v5
	v_max_u32_e32 v0, v2, v0
	v_min_u32_e32 v2, v1, v0
	v_max_u32_e32 v9, v1, v0
	v_add_u32_e32 v0, s40, v45
	v_ashrrev_i32_e32 v1, 31, v0
	v_lshlrev_b64 v[0:1], 10, v[0:1]
	v_readlane_b32 s16, v255, 50
	v_min_u32_e32 v30, v26, v27
	v_min_u32_e32 v28, v24, v25
	v_min_u32_e32 v22, v15, v17
	v_min_u32_e32 v18, v10, v11
	v_max_u32_e32 v26, v26, v27
	v_max_u32_e32 v24, v24, v25
	v_max_u32_e32 v15, v15, v17
	v_max_u32_e32 v10, v10, v11
	v_lshl_or_b32 v0, s39, 6, v0
	v_readlane_b32 s17, v255, 51
	v_min_u32_e32 v25, v26, v24
	v_min_u32_e32 v11, v15, v10
	v_max_u32_e32 v24, v26, v24
	v_max_u32_e32 v10, v15, v10
	v_lshl_add_u64 v[4:5], s[68:69], 0, v[0:1]
	v_lshl_add_u64 v[6:7], s[16:17], 0, v[0:1]
	v_and_b32_e32 v0, 0xffffff80, v2
	v_min_u32_e32 v15, v24, v10
	v_max_u32_e32 v10, v24, v10
	v_and_b32_e32 v1, 0xffffff80, v9
	v_and_b32_e32 v24, 0x7fffff80, v2
	v_xor_b32_e32 v0, -1, v0
	v_cmp_gt_i32_e32 vcc, 0, v2
	v_min_u32_e32 v17, v25, v11
	v_max_u32_e32 v11, v25, v11
	v_xor_b32_e32 v12, -1, v2
	v_and_b32_e32 v25, 0x7fffff80, v9
	v_xor_b32_e32 v26, -1, v1
	v_cndmask_b32_e32 v1, v0, v24, vcc
	v_cmp_gt_i32_e32 vcc, 0, v9
	v_and_b32_e32 v2, 0xffffff80, v3
	v_xor_b32_e32 v2, -1, v2
	v_cndmask_b32_e32 v0, v26, v25, vcc
	v_and_b32_e32 v25, 0xffffff80, v8
	v_and_b32_e32 v26, 0x7fffff80, v3
	v_cmp_gt_i32_e32 vcc, 0, v3
	v_xor_b32_e32 v13, -1, v9
	v_xor_b32_e32 v9, -1, v3
	v_and_b32_e32 v27, 0x7fffff80, v8
	v_xor_b32_e32 v25, -1, v25
	v_cndmask_b32_e32 v3, v2, v26, vcc
	v_cmp_gt_i32_e32 vcc, 0, v8
	v_xor_b32_e32 v24, -1, v8
	v_xor_b32_e32 v8, -1, v14
	v_cndmask_b32_e32 v2, v25, v27, vcc
	global_store_dwordx4 v[4:5], v[0:3], off
	v_cmp_gt_i32_e32 vcc, 0, v14
	v_min_u32_e32 v29, v30, v28
	v_and_b32_e32 v1, 0x7f, v12
	v_and_b32_e32 v0, 0x7f, v13
	v_and_b32_e32 v3, 0x7f, v9
	v_and_b32_e32 v2, 0x7f, v24
	global_store_dwordx4 v[6:7], v[0:3], off
	v_xor_b32_e32 v9, -1, v20
	v_xor_b32_e32 v13, -1, v16
	v_and_b32_e32 v0, 0xffffff80, v14
	v_and_b32_e32 v1, 0xffffff80, v20
	v_and_b32_e32 v2, 0x7fffff80, v14
	v_xor_b32_e32 v0, -1, v0
	v_and_b32_e32 v3, 0x7fffff80, v20
	v_xor_b32_e32 v12, -1, v1
	v_cndmask_b32_e32 v1, v0, v2, vcc
	v_cmp_gt_i32_e32 vcc, 0, v20
	v_and_b32_e32 v2, 0xffffff80, v21
	v_and_b32_e32 v14, 0x7fffff80, v21
	v_cndmask_b32_e32 v0, v12, v3, vcc
	v_and_b32_e32 v3, 0xffffff80, v16
	v_xor_b32_e32 v2, -1, v2
	v_cmp_gt_i32_e32 vcc, 0, v21
	v_and_b32_e32 v20, 0x7fffff80, v16
	v_xor_b32_e32 v24, -1, v3
	v_cndmask_b32_e32 v3, v2, v14, vcc
	v_cmp_gt_i32_e32 vcc, 0, v16
	v_xor_b32_e32 v12, -1, v21
	v_and_b32_e32 v14, 0x7fffff80, v11
	v_cndmask_b32_e32 v2, v24, v20, vcc
	global_store_dwordx4 v[4:5], v[0:3], off offset:16
	v_cmp_gt_i32_e32 vcc, 0, v15
	v_min_u32_e32 v19, v22, v18
	v_and_b32_e32 v1, 0x7f, v8
	v_and_b32_e32 v0, 0x7f, v9
	v_and_b32_e32 v3, 0x7f, v12
	v_and_b32_e32 v2, 0x7f, v13
	global_store_dwordx4 v[6:7], v[0:3], off offset:16
	v_and_b32_e32 v13, 0x7fffff80, v17
	v_xor_b32_e32 v8, -1, v15
	v_and_b32_e32 v0, 0xffffff80, v15
	v_and_b32_e32 v1, 0xffffff80, v10
	v_and_b32_e32 v2, 0x7fffff80, v15
	v_xor_b32_e32 v0, -1, v0
	v_and_b32_e32 v3, 0x7fffff80, v10
	v_xor_b32_e32 v12, -1, v1
	v_cndmask_b32_e32 v1, v0, v2, vcc
	v_cmp_gt_i32_e32 vcc, 0, v10
	v_and_b32_e32 v2, 0xffffff80, v17
	v_xor_b32_e32 v2, -1, v2
	v_cndmask_b32_e32 v0, v12, v3, vcc
	v_and_b32_e32 v3, 0xffffff80, v11
	v_cmp_gt_i32_e32 vcc, 0, v17
	v_xor_b32_e32 v15, -1, v3
	v_max_u32_e32 v28, v30, v28
	v_cndmask_b32_e32 v3, v2, v13, vcc
	v_cmp_gt_i32_e32 vcc, 0, v11
	v_max_u32_e32 v18, v22, v18
	v_xor_b32_e32 v9, -1, v10
	v_xor_b32_e32 v10, -1, v17
	v_xor_b32_e32 v12, -1, v11
	v_cndmask_b32_e32 v2, v15, v14, vcc
	v_min_u32_e32 v22, v28, v18
	global_store_dwordx4 v[4:5], v[0:3], off offset:32
	v_max_u32_e32 v18, v28, v18
	v_min_u32_e32 v23, v29, v19
	v_and_b32_e32 v1, 0x7f, v8
	v_and_b32_e32 v0, 0x7f, v9
	v_and_b32_e32 v3, 0x7f, v10
	v_and_b32_e32 v2, 0x7f, v12
	global_store_dwordx4 v[6:7], v[0:3], off offset:32
	v_cmp_gt_i32_e32 vcc, 0, v22
	v_max_u32_e32 v19, v29, v19
	v_and_b32_e32 v0, 0xffffff80, v22
	v_and_b32_e32 v1, 0xffffff80, v18
	v_and_b32_e32 v2, 0x7fffff80, v22
	v_xor_b32_e32 v0, -1, v0
	v_and_b32_e32 v3, 0x7fffff80, v18
	v_xor_b32_e32 v10, -1, v1
	v_cndmask_b32_e32 v1, v0, v2, vcc
	v_cmp_gt_i32_e32 vcc, 0, v18
	v_and_b32_e32 v2, 0xffffff80, v23
	v_and_b32_e32 v12, 0x7fffff80, v23
	v_cndmask_b32_e32 v0, v10, v3, vcc
	v_and_b32_e32 v3, 0xffffff80, v19
	v_xor_b32_e32 v2, -1, v2
	v_cmp_gt_i32_e32 vcc, 0, v23
	v_and_b32_e32 v13, 0x7fffff80, v19
	v_xor_b32_e32 v14, -1, v3
	v_cndmask_b32_e32 v3, v2, v12, vcc
	v_cmp_gt_i32_e32 vcc, 0, v19
	v_xor_b32_e32 v8, -1, v22
	v_xor_b32_e32 v9, -1, v18
	v_xor_b32_e32 v10, -1, v23
	v_xor_b32_e32 v11, -1, v19
	v_cndmask_b32_e32 v2, v14, v13, vcc
	global_store_dwordx4 v[4:5], v[0:3], off offset:48
	s_nop 1
	v_and_b32_e32 v1, 0x7f, v8
	v_and_b32_e32 v0, 0x7f, v9
	v_and_b32_e32 v3, 0x7f, v10
	v_and_b32_e32 v2, 0x7f, v11
	global_store_dwordx4 v[6:7], v[0:3], off offset:48
	s_branch .LBB0_1447

; DI int TID() { int t = threadIdx.x; asm volatile("" : "+v"(t)); return t; }
; DI void phase_peer(const Params& p, int l, int bid, int nblk) {
;     ...
;   for (int row = bid * 4 + w; row < ROWS; row += nblk * 4) {
;     const int b = row / TPB, pos = row % TPB;
;     if (l == 1 && pos < CTXL) continue;
;     const int lane = TID() & 63;
.Lpeer_a_again:
	v_mov_b32_e32 v0, v218
	s_mov_b32 s55, 0
	s_mov_b32 s66, 0
	v_readlane_b32 s0, v255, 58
	v_ashrrev_i32_e32 v0, 6, v0
	v_readlane_b32 s1, v255, 59
	v_add_u32_e32 v64, s0, v0
	s_mov_b32 s0, 0x9000
	v_cmp_gt_i32_e32 vcc, s0, v64
	s_and_saveexec_b64 s[50:51], vcc
	s_cbranch_execz .LBB0_1558
	s_mov_b64 s[62:63], 0
	s_branch .LBB0_1509
